# up epilogue: all 16 row-stat ds_bpermute hoisted to epilogue top into free regs, 7 lgkmcnt waits removed (on v12)
# baseline (speedup 1.0000x reference)
.Lup_sig_skip:
	v_mbcnt_lo_u32_b32 v177, -1, 0
	v_mbcnt_hi_u32_b32 v177, -1, v177
	s_lshl_b32 s3, s3, 11
	v_and_b32_e32 v180, 15, v177
	v_ashrrev_i32_e32 v183, 4, v177
	s_add_i32 s3, s53, s3
	v_lshlrev_b32_e32 v181, 2, v180
	ds_bpermute_b32 v182, v181, v176
	ds_bpermute_b32 v184, v181, v179
	ds_bpermute_b32 v202, v181, v179 offset:64
	ds_bpermute_b32 v204, v181, v176 offset:64
	ds_bpermute_b32 v206, v181, v179 offset:128
	ds_bpermute_b32 v208, v181, v176 offset:128
	ds_bpermute_b32 v210, v181, v179 offset:192
	ds_bpermute_b32 v212, v181, v176 offset:192
	ds_bpermute_b32 v214, v181, v174
	ds_bpermute_b32 v216, v181, v175
	ds_bpermute_b32 v218, v181, v175 offset:64
	ds_bpermute_b32 v220, v181, v174 offset:64
	ds_bpermute_b32 v224, v181, v175 offset:128
	ds_bpermute_b32 v226, v181, v174 offset:128
	ds_bpermute_b32 v228, v181, v175 offset:192
	ds_bpermute_b32 v230, v181, v174 offset:192
	v_lshl_add_u32 v114, v183, 5, s3
	ds_read_b128 v[142:145], v114
	ds_read_b128 v[122:125], v114 offset:16
	ds_read_b128 v[146:149], v114 offset:1024
	ds_read_b128 v[126:129], v114 offset:1040
	ds_read_b128 v[138:141], v114 offset:512
	ds_read_b128 v[110:113], v114 offset:528
	ds_read_b128 v[134:137], v114 offset:1536
	ds_read_b128 v[114:117], v114 offset:1552
	s_lshl_b32 s23, s36, 7
	s_waitcnt lgkmcnt(0)
	v_pk_fma_f32 v[158:159], v[142:143], v[182:183], v[158:159] op_sel_hi:[1,0,1] neg_lo:[1,0,0] neg_hi:[1,0,0]
	v_pk_fma_f32 v[160:161], v[144:145], v[182:183], v[160:161] op_sel_hi:[1,0,1] neg_lo:[1,0,0] neg_hi:[1,0,0]
	v_pk_fma_f32 v[198:199], v[158:159], v[184:185], v[146:147] op_sel_hi:[1,0,1]
	s_or_b32 s23, s23, s49
	v_mul_f32_e32 v158, 0xbfb8aa3b, v198
	v_exp_f32_e32 v158, v158
	v_mul_f32_e32 v159, 0xbfb8aa3b, v199
	v_exp_f32_e32 v159, v159
	v_pk_fma_f32 v[160:161], v[160:161], v[184:185], v[148:149] op_sel_hi:[1,0,1]
	v_add_f32_e32 v158, 1.0, v158
	v_lshl_add_u32 v196, v183, 3, s23
	v_rcp_f32_e32 v200, v158
	v_add_f32_e32 v158, 1.0, v159
	v_pk_fma_f32 v[154:155], v[138:139], v[182:183], v[154:155] op_sel_hi:[1,0,1] neg_lo:[1,0,0] neg_hi:[1,0,0]
	v_mul_f32_e32 v183, 0xbfb8aa3b, v160
	v_rcp_f32_e32 v201, v158
	v_pk_fma_f32 v[154:155], v[154:155], v[184:185], v[134:135] op_sel_hi:[1,0,1]
	v_exp_f32_e32 v183, v183
	v_mul_f32_e32 v185, 0xbfb8aa3b, v161
	v_exp_f32_e32 v185, v185
	v_ashrrev_i32_e32 v197, 31, v196
	v_lshl_add_u64 v[158:159], v[196:197], 1, s[92:93]
	v_pk_mul_f32 v[196:197], v[198:199], v[200:201]
	v_add_f32_e32 v183, 1.0, v183
	v_pk_mul_f32 v[154:155], v[154:155], v[196:197]
	v_rcp_f32_e32 v196, v183
	v_pk_fma_f32 v[156:157], v[140:141], v[182:183], v[156:157] op_sel_hi:[1,0,1] neg_lo:[1,0,0] neg_hi:[1,0,0]
	v_add_f32_e32 v183, 1.0, v185
	v_rcp_f32_e32 v197, v183
	v_pk_fma_f32 v[150:151], v[122:123], v[182:183], v[150:151] op_sel_hi:[1,0,1] neg_lo:[1,0,0] neg_hi:[1,0,0]
	v_pk_fma_f32 v[156:157], v[156:157], v[184:185], v[136:137] op_sel_hi:[1,0,1]
	v_pk_fma_f32 v[150:151], v[150:151], v[184:185], v[126:127] op_sel_hi:[1,0,1]
	v_pk_mul_f32 v[160:161], v[160:161], v[196:197]
	v_mul_f32_e32 v183, 0xbfb8aa3b, v150
	v_exp_f32_e32 v183, v183
	v_pk_mul_f32 v[156:157], v[156:157], v[160:161]
	v_mul_f32_e32 v161, 0xbfb8aa3b, v151
	v_exp_f32_e32 v161, v161
	v_pk_fma_f32 v[152:153], v[124:125], v[182:183], v[152:153] op_sel_hi:[1,0,1] neg_lo:[1,0,0] neg_hi:[1,0,0]
	v_pk_fma_f32 v[130:131], v[110:111], v[182:183], v[130:131] op_sel_hi:[1,0,1] neg_lo:[1,0,0] neg_hi:[1,0,0]
	v_pk_fma_f32 v[152:153], v[152:153], v[184:185], v[128:129] op_sel_hi:[1,0,1]
	v_add_f32_e32 v160, 1.0, v183
	v_pk_fma_f32 v[130:131], v[130:131], v[184:185], v[114:115] op_sel_hi:[1,0,1]
	v_add_f32_e32 v161, 1.0, v161
	v_mul_f32_e32 v183, 0xbfb8aa3b, v152
	v_mul_f32_e32 v185, 0xbfb8aa3b, v153
	v_rcp_f32_e32 v160, v160
	v_rcp_f32_e32 v161, v161
	v_exp_f32_e32 v183, v183
	v_exp_f32_e32 v185, v185
	s_lshl_b32 s3, s30, 8
	v_pk_mul_f32 v[150:151], v[150:151], v[160:161]
	v_add_f32_e32 v160, 1.0, v183
	v_add_f32_e32 v161, 1.0, v185
	v_rcp_f32_e32 v160, v160
	v_rcp_f32_e32 v161, v161
	v_pk_mul_f32 v[150:151], v[130:131], v[150:151]
	v_pk_fma_f32 v[130:131], v[112:113], v[182:183], v[132:133] op_sel_hi:[1,0,1] neg_lo:[1,0,0] neg_hi:[1,0,0]
	s_add_i32 s3, s3, s45
	v_pk_fma_f32 v[130:131], v[130:131], v[184:185], v[116:117] op_sel_hi:[1,0,1]
	v_pk_mul_f32 v[132:133], v[152:153], v[160:161]
	v_pk_mul_f32 v[152:153], v[130:131], v[132:133]
	v_cvt_pk_bf16_f32 v130, v154, v155
	v_cvt_pk_bf16_f32 v132, v150, v151
	v_cvt_pk_bf16_f32 v133, v152, v153
	v_add_u32_e32 v180, s3, v180
	v_cvt_pk_bf16_f32 v131, v156, v157
	v_pk_fma_f32 v[118:119], v[142:143], v[204:205], v[118:119] op_sel_hi:[1,0,1] neg_lo:[1,0,0] neg_hi:[1,0,0]
	v_pk_fma_f32 v[106:107], v[138:139], v[204:205], v[106:107] op_sel_hi:[1,0,1] neg_lo:[1,0,0] neg_hi:[1,0,0]
	v_pk_fma_f32 v[118:119], v[118:119], v[202:203], v[146:147] op_sel_hi:[1,0,1]
	v_pk_fma_f32 v[120:121], v[144:145], v[204:205], v[120:121] op_sel_hi:[1,0,1] neg_lo:[1,0,0] neg_hi:[1,0,0]
	v_mul_f32_e32 v150, 0xbfb8aa3b, v118
	v_exp_f32_e32 v152, v150
	v_mul_f32_e32 v150, 0xbfb8aa3b, v119
	v_exp_f32_e32 v153, v150
	v_mad_i64_i32 v[150:151], s[38:39], v180, s65, v[158:159]
	v_add_f32_e32 v152, 1.0, v152
	v_add_f32_e32 v153, 1.0, v153
	v_rcp_f32_e32 v152, v152
	v_rcp_f32_e32 v153, v153
	v_pk_fma_f32 v[106:107], v[106:107], v[202:203], v[134:135] op_sel_hi:[1,0,1]
	v_pk_fma_f32 v[120:121], v[120:121], v[202:203], v[148:149] op_sel_hi:[1,0,1]
	global_store_dwordx4 v[150:151], v[130:133], off sc1
	v_pk_mul_f32 v[118:119], v[118:119], v[152:153]
	v_pk_fma_f32 v[108:109], v[140:141], v[204:205], v[108:109] op_sel_hi:[1,0,1] neg_lo:[1,0,0] neg_hi:[1,0,0]
	v_mul_f32_e32 v130, 0xbfb8aa3b, v120
	v_pk_mul_f32 v[106:107], v[106:107], v[118:119]
	v_mul_f32_e32 v118, 0xbfb8aa3b, v121
	v_exp_f32_e32 v130, v130
	v_exp_f32_e32 v119, v118
	v_pk_fma_f32 v[102:103], v[122:123], v[204:205], v[102:103] op_sel_hi:[1,0,1] neg_lo:[1,0,0] neg_hi:[1,0,0]
	v_pk_fma_f32 v[108:109], v[108:109], v[202:203], v[136:137] op_sel_hi:[1,0,1]
	v_add_f32_e32 v118, 1.0, v130
	v_add_f32_e32 v119, 1.0, v119
	v_rcp_f32_e32 v118, v118
	v_rcp_f32_e32 v119, v119
	v_pk_fma_f32 v[102:103], v[102:103], v[202:203], v[126:127] op_sel_hi:[1,0,1]
	v_pk_fma_f32 v[104:105], v[124:125], v[204:205], v[104:105] op_sel_hi:[1,0,1] neg_lo:[1,0,0] neg_hi:[1,0,0]
	v_mul_f32_e32 v130, 0xbfb8aa3b, v102
	v_pk_mul_f32 v[118:119], v[120:121], v[118:119]
	v_exp_f32_e32 v130, v130
	v_pk_mul_f32 v[108:109], v[108:109], v[118:119]
	v_mul_f32_e32 v119, 0xbfb8aa3b, v103
	v_exp_f32_e32 v119, v119
	v_pk_fma_f32 v[104:105], v[104:105], v[202:203], v[128:129] op_sel_hi:[1,0,1]
	v_add_f32_e32 v118, 1.0, v130
	v_mul_f32_e32 v120, 0xbfb8aa3b, v104
	v_add_f32_e32 v119, 1.0, v119
	v_mul_f32_e32 v121, 0xbfb8aa3b, v105
	v_rcp_f32_e32 v118, v118
	v_rcp_f32_e32 v119, v119
	v_exp_f32_e32 v120, v120
	v_exp_f32_e32 v121, v121
	v_pk_fma_f32 v[98:99], v[110:111], v[204:205], v[98:99] op_sel_hi:[1,0,1] neg_lo:[1,0,0] neg_hi:[1,0,0]
	v_pk_mul_f32 v[102:103], v[102:103], v[118:119]
	v_add_f32_e32 v118, 1.0, v120
	v_add_f32_e32 v119, 1.0, v121
	v_rcp_f32_e32 v118, v118
	v_rcp_f32_e32 v119, v119
	v_pk_fma_f32 v[98:99], v[98:99], v[202:203], v[114:115] op_sel_hi:[1,0,1]
	s_andn2_b64 vcc, exec, s[0:1]
	v_pk_mul_f32 v[102:103], v[98:99], v[102:103]
	v_pk_fma_f32 v[98:99], v[112:113], v[204:205], v[100:101] op_sel_hi:[1,0,1] neg_lo:[1,0,0] neg_hi:[1,0,0]
	v_pk_mul_f32 v[100:101], v[104:105], v[118:119]
	v_pk_fma_f32 v[98:99], v[98:99], v[202:203], v[116:117] op_sel_hi:[1,0,1]
	v_pk_mul_f32 v[104:105], v[98:99], v[100:101]
	v_cvt_pk_bf16_f32 v98, v106, v107
	v_add_u32_e32 v119, 16, v180
	v_cvt_pk_bf16_f32 v100, v102, v103
	v_cvt_pk_bf16_f32 v101, v104, v105
	v_cvt_pk_bf16_f32 v99, v108, v109
	v_pk_fma_f32 v[94:95], v[142:143], v[208:209], v[94:95] op_sel_hi:[1,0,1] neg_lo:[1,0,0] neg_hi:[1,0,0]
	v_pk_fma_f32 v[90:91], v[138:139], v[208:209], v[90:91] op_sel_hi:[1,0,1] neg_lo:[1,0,0] neg_hi:[1,0,0]
	v_pk_fma_f32 v[94:95], v[94:95], v[206:207], v[146:147] op_sel_hi:[1,0,1]
	v_pk_fma_f32 v[96:97], v[144:145], v[208:209], v[96:97] op_sel_hi:[1,0,1] neg_lo:[1,0,0] neg_hi:[1,0,0]
	v_mul_f32_e32 v102, 0xbfb8aa3b, v94
	v_exp_f32_e32 v104, v102
	v_mul_f32_e32 v102, 0xbfb8aa3b, v95
	v_exp_f32_e32 v105, v102
	v_mad_i64_i32 v[102:103], s[38:39], v119, s65, v[158:159]
	v_add_f32_e32 v104, 1.0, v104
	v_add_f32_e32 v105, 1.0, v105
	v_rcp_f32_e32 v104, v104
	v_rcp_f32_e32 v105, v105
	v_pk_fma_f32 v[90:91], v[90:91], v[206:207], v[134:135] op_sel_hi:[1,0,1]
	v_pk_fma_f32 v[96:97], v[96:97], v[206:207], v[148:149] op_sel_hi:[1,0,1]
	global_store_dwordx4 v[102:103], v[98:101], off sc1
	v_pk_mul_f32 v[94:95], v[94:95], v[104:105]
	v_pk_fma_f32 v[92:93], v[140:141], v[208:209], v[92:93] op_sel_hi:[1,0,1] neg_lo:[1,0,0] neg_hi:[1,0,0]
	v_mul_f32_e32 v98, 0xbfb8aa3b, v96
	v_pk_mul_f32 v[90:91], v[90:91], v[94:95]
	v_mul_f32_e32 v94, 0xbfb8aa3b, v97
	v_exp_f32_e32 v98, v98
	v_exp_f32_e32 v95, v94
	v_pk_fma_f32 v[86:87], v[122:123], v[208:209], v[86:87] op_sel_hi:[1,0,1] neg_lo:[1,0,0] neg_hi:[1,0,0]
	v_pk_fma_f32 v[92:93], v[92:93], v[206:207], v[136:137] op_sel_hi:[1,0,1]
	v_add_f32_e32 v94, 1.0, v98
	v_add_f32_e32 v95, 1.0, v95
	v_rcp_f32_e32 v94, v94
	v_rcp_f32_e32 v95, v95
	v_pk_fma_f32 v[86:87], v[86:87], v[206:207], v[126:127] op_sel_hi:[1,0,1]
	v_pk_fma_f32 v[88:89], v[124:125], v[208:209], v[88:89] op_sel_hi:[1,0,1] neg_lo:[1,0,0] neg_hi:[1,0,0]
	v_mul_f32_e32 v98, 0xbfb8aa3b, v86
	v_pk_mul_f32 v[94:95], v[96:97], v[94:95]
	v_exp_f32_e32 v98, v98
	v_pk_mul_f32 v[92:93], v[92:93], v[94:95]
	v_mul_f32_e32 v95, 0xbfb8aa3b, v87
	v_exp_f32_e32 v95, v95
	v_pk_fma_f32 v[88:89], v[88:89], v[206:207], v[128:129] op_sel_hi:[1,0,1]
	v_add_f32_e32 v94, 1.0, v98
	v_mul_f32_e32 v96, 0xbfb8aa3b, v88
	v_add_f32_e32 v95, 1.0, v95
	v_mul_f32_e32 v97, 0xbfb8aa3b, v89
	v_rcp_f32_e32 v94, v94
	v_rcp_f32_e32 v95, v95
	v_exp_f32_e32 v96, v96
	v_exp_f32_e32 v97, v97
	v_pk_fma_f32 v[82:83], v[110:111], v[208:209], v[82:83] op_sel_hi:[1,0,1] neg_lo:[1,0,0] neg_hi:[1,0,0]
	v_pk_mul_f32 v[86:87], v[86:87], v[94:95]
	v_add_f32_e32 v94, 1.0, v96
	v_add_f32_e32 v95, 1.0, v97
	v_rcp_f32_e32 v94, v94
	v_rcp_f32_e32 v95, v95
	v_pk_fma_f32 v[82:83], v[82:83], v[206:207], v[114:115] op_sel_hi:[1,0,1]
	s_mov_b64 s[0:1], -1
	v_pk_mul_f32 v[86:87], v[82:83], v[86:87]
	v_pk_fma_f32 v[82:83], v[112:113], v[208:209], v[84:85] op_sel_hi:[1,0,1] neg_lo:[1,0,0] neg_hi:[1,0,0]
	v_pk_mul_f32 v[84:85], v[88:89], v[94:95]
	v_pk_fma_f32 v[82:83], v[82:83], v[206:207], v[116:117] op_sel_hi:[1,0,1]
	v_pk_mul_f32 v[88:89], v[82:83], v[84:85]
	v_cvt_pk_bf16_f32 v82, v90, v91
	v_add_u32_e32 v95, 32, v180
	v_cvt_pk_bf16_f32 v84, v86, v87
	v_cvt_pk_bf16_f32 v85, v88, v89
	v_cvt_pk_bf16_f32 v83, v92, v93
	v_pk_fma_f32 v[78:79], v[142:143], v[212:213], v[78:79] op_sel_hi:[1,0,1] neg_lo:[1,0,0] neg_hi:[1,0,0]
	v_pk_fma_f32 v[74:75], v[138:139], v[212:213], v[74:75] op_sel_hi:[1,0,1] neg_lo:[1,0,0] neg_hi:[1,0,0]
	v_pk_fma_f32 v[78:79], v[78:79], v[210:211], v[146:147] op_sel_hi:[1,0,1]
	v_pk_fma_f32 v[80:81], v[144:145], v[212:213], v[80:81] op_sel_hi:[1,0,1] neg_lo:[1,0,0] neg_hi:[1,0,0]
	v_mul_f32_e32 v86, 0xbfb8aa3b, v78
	v_exp_f32_e32 v88, v86
	v_mul_f32_e32 v86, 0xbfb8aa3b, v79
	v_exp_f32_e32 v89, v86
	v_mad_i64_i32 v[86:87], s[38:39], v95, s65, v[158:159]
	v_add_f32_e32 v88, 1.0, v88
	v_add_f32_e32 v89, 1.0, v89
	v_rcp_f32_e32 v88, v88
	v_rcp_f32_e32 v89, v89
	v_pk_fma_f32 v[74:75], v[74:75], v[210:211], v[134:135] op_sel_hi:[1,0,1]
	v_pk_fma_f32 v[80:81], v[80:81], v[210:211], v[148:149] op_sel_hi:[1,0,1]
	global_store_dwordx4 v[86:87], v[82:85], off sc1
	v_pk_mul_f32 v[78:79], v[78:79], v[88:89]
	v_pk_fma_f32 v[76:77], v[140:141], v[212:213], v[76:77] op_sel_hi:[1,0,1] neg_lo:[1,0,0] neg_hi:[1,0,0]
	v_mul_f32_e32 v82, 0xbfb8aa3b, v80
	v_pk_mul_f32 v[74:75], v[74:75], v[78:79]
	v_mul_f32_e32 v78, 0xbfb8aa3b, v81
	v_exp_f32_e32 v82, v82
	v_exp_f32_e32 v79, v78
	v_pk_fma_f32 v[70:71], v[122:123], v[212:213], v[70:71] op_sel_hi:[1,0,1] neg_lo:[1,0,0] neg_hi:[1,0,0]
	v_pk_fma_f32 v[76:77], v[76:77], v[210:211], v[136:137] op_sel_hi:[1,0,1]
	v_add_f32_e32 v78, 1.0, v82
	v_add_f32_e32 v79, 1.0, v79
	v_rcp_f32_e32 v78, v78
	v_rcp_f32_e32 v79, v79
	v_pk_fma_f32 v[70:71], v[70:71], v[210:211], v[126:127] op_sel_hi:[1,0,1]
	v_pk_fma_f32 v[72:73], v[124:125], v[212:213], v[72:73] op_sel_hi:[1,0,1] neg_lo:[1,0,0] neg_hi:[1,0,0]
	v_mul_f32_e32 v82, 0xbfb8aa3b, v70
	v_pk_mul_f32 v[78:79], v[80:81], v[78:79]
	v_exp_f32_e32 v82, v82
	v_pk_mul_f32 v[76:77], v[76:77], v[78:79]
	v_mul_f32_e32 v79, 0xbfb8aa3b, v71
	v_exp_f32_e32 v79, v79
	v_pk_fma_f32 v[72:73], v[72:73], v[210:211], v[128:129] op_sel_hi:[1,0,1]
	v_add_f32_e32 v78, 1.0, v82
	v_mul_f32_e32 v80, 0xbfb8aa3b, v72
	v_add_f32_e32 v79, 1.0, v79
	v_mul_f32_e32 v81, 0xbfb8aa3b, v73
	v_rcp_f32_e32 v78, v78
	v_rcp_f32_e32 v79, v79
	v_exp_f32_e32 v80, v80
	v_exp_f32_e32 v81, v81
	v_pk_fma_f32 v[66:67], v[110:111], v[212:213], v[66:67] op_sel_hi:[1,0,1] neg_lo:[1,0,0] neg_hi:[1,0,0]
	v_pk_mul_f32 v[70:71], v[70:71], v[78:79]
	v_add_f32_e32 v78, 1.0, v80
	v_add_f32_e32 v79, 1.0, v81
	v_rcp_f32_e32 v78, v78
	v_rcp_f32_e32 v79, v79
	v_pk_fma_f32 v[66:67], v[66:67], v[210:211], v[114:115] op_sel_hi:[1,0,1]
	s_nop 0
	v_pk_mul_f32 v[70:71], v[66:67], v[70:71]
	v_pk_fma_f32 v[66:67], v[112:113], v[212:213], v[68:69] op_sel_hi:[1,0,1] neg_lo:[1,0,0] neg_hi:[1,0,0]
	v_pk_mul_f32 v[68:69], v[72:73], v[78:79]
	v_pk_fma_f32 v[66:67], v[66:67], v[210:211], v[116:117] op_sel_hi:[1,0,1]
	v_add_u32_e32 v78, 48, v180
	v_pk_mul_f32 v[72:73], v[66:67], v[68:69]
	v_cvt_pk_bf16_f32 v68, v70, v71
	v_cvt_pk_bf16_f32 v66, v74, v75
	v_cvt_pk_bf16_f32 v67, v76, v77
	v_cvt_pk_bf16_f32 v69, v72, v73
	v_pk_fma_f32 v[62:63], v[142:143], v[214:215], v[62:63] op_sel_hi:[1,0,1] neg_lo:[1,0,0] neg_hi:[1,0,0]
	v_mad_i64_i32 v[72:73], s[38:39], v78, s65, v[158:159]
	v_pk_fma_f32 v[62:63], v[62:63], v[216:217], v[146:147] op_sel_hi:[1,0,1]
	global_store_dwordx4 v[72:73], v[66:69], off sc1
	v_mul_f32_e32 v71, 0xbfb8aa3b, v62
	v_mul_f32_e32 v75, 0xbfb8aa3b, v63
	v_exp_f32_e32 v71, v71
	v_exp_f32_e32 v75, v75
	v_add_u32_e32 v68, 0x80, v180
	v_add_f32_e32 v66, 1.0, v71
	v_add_f32_e32 v67, 1.0, v75
	v_rcp_f32_e32 v66, v66
	v_rcp_f32_e32 v67, v67
	v_pk_fma_f32 v[58:59], v[138:139], v[214:215], v[58:59] op_sel_hi:[1,0,1] neg_lo:[1,0,0] neg_hi:[1,0,0]
	v_pk_fma_f32 v[64:65], v[144:145], v[214:215], v[64:65] op_sel_hi:[1,0,1] neg_lo:[1,0,0] neg_hi:[1,0,0]
	v_pk_fma_f32 v[58:59], v[58:59], v[216:217], v[134:135] op_sel_hi:[1,0,1]
	v_pk_mul_f32 v[62:63], v[62:63], v[66:67]
	v_pk_fma_f32 v[64:65], v[64:65], v[216:217], v[148:149] op_sel_hi:[1,0,1]
	v_pk_mul_f32 v[58:59], v[58:59], v[62:63]
	v_mul_f32_e32 v66, 0xbfb8aa3b, v64
	v_mul_f32_e32 v62, 0xbfb8aa3b, v65
	v_exp_f32_e32 v66, v66
	v_exp_f32_e32 v63, v62
	v_pk_fma_f32 v[60:61], v[140:141], v[214:215], v[60:61] op_sel_hi:[1,0,1] neg_lo:[1,0,0] neg_hi:[1,0,0]
	v_pk_fma_f32 v[54:55], v[122:123], v[214:215], v[54:55] op_sel_hi:[1,0,1] neg_lo:[1,0,0] neg_hi:[1,0,0]
	v_add_f32_e32 v62, 1.0, v66
	v_add_f32_e32 v63, 1.0, v63
	v_rcp_f32_e32 v62, v62
	v_rcp_f32_e32 v63, v63
	v_pk_fma_f32 v[54:55], v[54:55], v[216:217], v[126:127] op_sel_hi:[1,0,1]
	v_pk_fma_f32 v[60:61], v[60:61], v[216:217], v[136:137] op_sel_hi:[1,0,1]
	v_mul_f32_e32 v66, 0xbfb8aa3b, v54
	v_pk_mul_f32 v[62:63], v[64:65], v[62:63]
	v_exp_f32_e32 v66, v66
	v_pk_mul_f32 v[60:61], v[60:61], v[62:63]
	v_mul_f32_e32 v63, 0xbfb8aa3b, v55
	v_exp_f32_e32 v63, v63
	v_pk_fma_f32 v[56:57], v[124:125], v[214:215], v[56:57] op_sel_hi:[1,0,1] neg_lo:[1,0,0] neg_hi:[1,0,0]
	v_add_f32_e32 v62, 1.0, v66
	v_pk_fma_f32 v[56:57], v[56:57], v[216:217], v[128:129] op_sel_hi:[1,0,1]
	v_add_f32_e32 v63, 1.0, v63
	v_mul_f32_e32 v64, 0xbfb8aa3b, v56
	v_mul_f32_e32 v65, 0xbfb8aa3b, v57
	v_rcp_f32_e32 v62, v62
	v_rcp_f32_e32 v63, v63
	v_exp_f32_e32 v64, v64
	v_exp_f32_e32 v65, v65
	v_pk_fma_f32 v[50:51], v[110:111], v[214:215], v[50:51] op_sel_hi:[1,0,1] neg_lo:[1,0,0] neg_hi:[1,0,0]
	v_pk_mul_f32 v[54:55], v[54:55], v[62:63]
	v_add_f32_e32 v62, 1.0, v64
	v_add_f32_e32 v63, 1.0, v65
	v_rcp_f32_e32 v62, v62
	v_rcp_f32_e32 v63, v63
	v_pk_fma_f32 v[50:51], v[50:51], v[216:217], v[114:115] op_sel_hi:[1,0,1]
	s_nop 0
	v_pk_mul_f32 v[54:55], v[50:51], v[54:55]
	v_pk_fma_f32 v[50:51], v[112:113], v[214:215], v[52:53] op_sel_hi:[1,0,1] neg_lo:[1,0,0] neg_hi:[1,0,0]
	v_pk_mul_f32 v[52:53], v[56:57], v[62:63]
	v_pk_fma_f32 v[50:51], v[50:51], v[216:217], v[116:117] op_sel_hi:[1,0,1]
	v_pk_mul_f32 v[56:57], v[50:51], v[52:53]
	v_cvt_pk_bf16_f32 v50, v58, v59
	v_cvt_pk_bf16_f32 v52, v54, v55
	v_cvt_pk_bf16_f32 v53, v56, v57
	v_cvt_pk_bf16_f32 v51, v60, v61
	v_pk_fma_f32 v[46:47], v[142:143], v[220:221], v[46:47] op_sel_hi:[1,0,1] neg_lo:[1,0,0] neg_hi:[1,0,0]
	s_nop 0
	v_pk_fma_f32 v[46:47], v[46:47], v[218:219], v[146:147] op_sel_hi:[1,0,1]
	v_pk_fma_f32 v[42:43], v[138:139], v[220:221], v[42:43] op_sel_hi:[1,0,1] neg_lo:[1,0,0] neg_hi:[1,0,0]
	v_mul_f32_e32 v54, 0xbfb8aa3b, v46
	v_exp_f32_e32 v56, v54
	v_mul_f32_e32 v54, 0xbfb8aa3b, v47
	v_exp_f32_e32 v57, v54
	v_pk_fma_f32 v[48:49], v[144:145], v[220:221], v[48:49] op_sel_hi:[1,0,1] neg_lo:[1,0,0] neg_hi:[1,0,0]
	v_add_f32_e32 v56, 1.0, v56
	v_rcp_f32_e32 v56, v56
	v_add_f32_e32 v57, 1.0, v57
	v_rcp_f32_e32 v57, v57
	v_mad_i64_i32 v[54:55], s[38:39], v68, s65, v[158:159]
	v_pk_fma_f32 v[42:43], v[42:43], v[218:219], v[134:135] op_sel_hi:[1,0,1]
	v_pk_mul_f32 v[46:47], v[46:47], v[56:57]
	v_pk_fma_f32 v[48:49], v[48:49], v[218:219], v[148:149] op_sel_hi:[1,0,1]
	global_store_dwordx4 v[54:55], v[50:53], off sc1
	v_pk_mul_f32 v[42:43], v[42:43], v[46:47]
	v_mul_f32_e32 v46, 0xbfb8aa3b, v49
	v_mul_f32_e32 v50, 0xbfb8aa3b, v48
	v_exp_f32_e32 v50, v50
	v_exp_f32_e32 v47, v46
	v_pk_fma_f32 v[44:45], v[140:141], v[220:221], v[44:45] op_sel_hi:[1,0,1] neg_lo:[1,0,0] neg_hi:[1,0,0]
	v_pk_fma_f32 v[38:39], v[122:123], v[220:221], v[38:39] op_sel_hi:[1,0,1] neg_lo:[1,0,0] neg_hi:[1,0,0]
	v_add_f32_e32 v46, 1.0, v50
	v_add_f32_e32 v47, 1.0, v47
	v_rcp_f32_e32 v46, v46
	v_rcp_f32_e32 v47, v47
	v_pk_fma_f32 v[38:39], v[38:39], v[218:219], v[126:127] op_sel_hi:[1,0,1]
	v_pk_fma_f32 v[44:45], v[44:45], v[218:219], v[136:137] op_sel_hi:[1,0,1]
	v_mul_f32_e32 v50, 0xbfb8aa3b, v38
	v_pk_mul_f32 v[46:47], v[48:49], v[46:47]
	v_exp_f32_e32 v50, v50
	v_pk_mul_f32 v[44:45], v[44:45], v[46:47]
	v_mul_f32_e32 v47, 0xbfb8aa3b, v39
	v_exp_f32_e32 v47, v47
	v_pk_fma_f32 v[40:41], v[124:125], v[220:221], v[40:41] op_sel_hi:[1,0,1] neg_lo:[1,0,0] neg_hi:[1,0,0]
	v_add_f32_e32 v46, 1.0, v50
	v_pk_fma_f32 v[40:41], v[40:41], v[218:219], v[128:129] op_sel_hi:[1,0,1]
	v_add_f32_e32 v47, 1.0, v47
	v_mul_f32_e32 v48, 0xbfb8aa3b, v40
	v_mul_f32_e32 v49, 0xbfb8aa3b, v41
	v_rcp_f32_e32 v46, v46
	v_rcp_f32_e32 v47, v47
	v_exp_f32_e32 v48, v48
	v_exp_f32_e32 v49, v49
	v_pk_fma_f32 v[34:35], v[110:111], v[220:221], v[34:35] op_sel_hi:[1,0,1] neg_lo:[1,0,0] neg_hi:[1,0,0]
	v_pk_mul_f32 v[38:39], v[38:39], v[46:47]
	v_add_f32_e32 v46, 1.0, v48
	v_add_f32_e32 v47, 1.0, v49
	v_rcp_f32_e32 v46, v46
	v_rcp_f32_e32 v47, v47
	v_pk_fma_f32 v[34:35], v[34:35], v[218:219], v[114:115] op_sel_hi:[1,0,1]
	s_nop 0
	v_pk_mul_f32 v[38:39], v[34:35], v[38:39]
	v_pk_fma_f32 v[34:35], v[112:113], v[220:221], v[36:37] op_sel_hi:[1,0,1] neg_lo:[1,0,0] neg_hi:[1,0,0]
	v_pk_mul_f32 v[36:37], v[40:41], v[46:47]
	v_pk_fma_f32 v[34:35], v[34:35], v[218:219], v[116:117] op_sel_hi:[1,0,1]
	v_pk_mul_f32 v[40:41], v[34:35], v[36:37]
	v_cvt_pk_bf16_f32 v34, v42, v43
	v_add_u32_e32 v47, 0x90, v180
	v_cvt_pk_bf16_f32 v36, v38, v39
	v_cvt_pk_bf16_f32 v37, v40, v41
	v_cvt_pk_bf16_f32 v35, v44, v45
	v_pk_fma_f32 v[30:31], v[142:143], v[226:227], v[30:31] op_sel_hi:[1,0,1] neg_lo:[1,0,0] neg_hi:[1,0,0]
	v_pk_fma_f32 v[26:27], v[138:139], v[226:227], v[26:27] op_sel_hi:[1,0,1] neg_lo:[1,0,0] neg_hi:[1,0,0]
	v_pk_fma_f32 v[30:31], v[30:31], v[224:225], v[146:147] op_sel_hi:[1,0,1]
	v_pk_fma_f32 v[32:33], v[144:145], v[226:227], v[32:33] op_sel_hi:[1,0,1] neg_lo:[1,0,0] neg_hi:[1,0,0]
	v_mul_f32_e32 v38, 0xbfb8aa3b, v30
	v_exp_f32_e32 v40, v38
	v_mul_f32_e32 v38, 0xbfb8aa3b, v31
	v_exp_f32_e32 v41, v38
	v_mad_i64_i32 v[38:39], s[38:39], v47, s65, v[158:159]
	v_add_f32_e32 v40, 1.0, v40
	v_add_f32_e32 v41, 1.0, v41
	v_rcp_f32_e32 v40, v40
	v_rcp_f32_e32 v41, v41
	v_pk_fma_f32 v[26:27], v[26:27], v[224:225], v[134:135] op_sel_hi:[1,0,1]
	v_pk_fma_f32 v[32:33], v[32:33], v[224:225], v[148:149] op_sel_hi:[1,0,1]
	global_store_dwordx4 v[38:39], v[34:37], off sc1
	v_pk_mul_f32 v[30:31], v[30:31], v[40:41]
	v_pk_fma_f32 v[28:29], v[140:141], v[226:227], v[28:29] op_sel_hi:[1,0,1] neg_lo:[1,0,0] neg_hi:[1,0,0]
	v_mul_f32_e32 v34, 0xbfb8aa3b, v32
	v_pk_mul_f32 v[26:27], v[26:27], v[30:31]
	v_mul_f32_e32 v30, 0xbfb8aa3b, v33
	v_exp_f32_e32 v34, v34
	v_exp_f32_e32 v31, v30
	v_pk_fma_f32 v[22:23], v[122:123], v[226:227], v[22:23] op_sel_hi:[1,0,1] neg_lo:[1,0,0] neg_hi:[1,0,0]
	v_pk_fma_f32 v[28:29], v[28:29], v[224:225], v[136:137] op_sel_hi:[1,0,1]
	v_add_f32_e32 v30, 1.0, v34
	v_add_f32_e32 v31, 1.0, v31
	v_rcp_f32_e32 v30, v30
	v_rcp_f32_e32 v31, v31
	v_pk_fma_f32 v[22:23], v[22:23], v[224:225], v[126:127] op_sel_hi:[1,0,1]
	v_pk_fma_f32 v[24:25], v[124:125], v[226:227], v[24:25] op_sel_hi:[1,0,1] neg_lo:[1,0,0] neg_hi:[1,0,0]
	v_mul_f32_e32 v34, 0xbfb8aa3b, v22
	v_pk_mul_f32 v[30:31], v[32:33], v[30:31]
	v_exp_f32_e32 v34, v34
	v_pk_mul_f32 v[28:29], v[28:29], v[30:31]
	v_mul_f32_e32 v31, 0xbfb8aa3b, v23
	v_exp_f32_e32 v31, v31
	v_pk_fma_f32 v[24:25], v[24:25], v[224:225], v[128:129] op_sel_hi:[1,0,1]
	v_add_f32_e32 v30, 1.0, v34
	v_mul_f32_e32 v32, 0xbfb8aa3b, v24
	v_add_f32_e32 v31, 1.0, v31
	v_mul_f32_e32 v33, 0xbfb8aa3b, v25
	v_rcp_f32_e32 v30, v30
	v_rcp_f32_e32 v31, v31
	v_exp_f32_e32 v32, v32
	v_exp_f32_e32 v33, v33
	v_pk_fma_f32 v[18:19], v[110:111], v[226:227], v[18:19] op_sel_hi:[1,0,1] neg_lo:[1,0,0] neg_hi:[1,0,0]
	v_pk_mul_f32 v[22:23], v[22:23], v[30:31]
	v_add_f32_e32 v30, 1.0, v32
	v_add_f32_e32 v31, 1.0, v33
	v_rcp_f32_e32 v30, v30
	v_rcp_f32_e32 v31, v31
	v_pk_fma_f32 v[18:19], v[18:19], v[224:225], v[114:115] op_sel_hi:[1,0,1]
	s_nop 0
	v_pk_mul_f32 v[22:23], v[18:19], v[22:23]
	v_pk_fma_f32 v[18:19], v[112:113], v[226:227], v[20:21] op_sel_hi:[1,0,1] neg_lo:[1,0,0] neg_hi:[1,0,0]
	v_pk_mul_f32 v[20:21], v[24:25], v[30:31]
	v_pk_fma_f32 v[18:19], v[18:19], v[224:225], v[116:117] op_sel_hi:[1,0,1]
	v_pk_mul_f32 v[24:25], v[18:19], v[20:21]
	v_cvt_pk_bf16_f32 v18, v26, v27
	v_add_u32_e32 v31, 0xa0, v180
	v_cvt_pk_bf16_f32 v20, v22, v23
	v_cvt_pk_bf16_f32 v21, v24, v25
	v_cvt_pk_bf16_f32 v19, v28, v29
	v_pk_fma_f32 v[14:15], v[142:143], v[230:231], v[14:15] op_sel_hi:[1,0,1] neg_lo:[1,0,0] neg_hi:[1,0,0]
	v_pk_fma_f32 v[10:11], v[138:139], v[230:231], v[10:11] op_sel_hi:[1,0,1] neg_lo:[1,0,0] neg_hi:[1,0,0]
	v_pk_fma_f32 v[14:15], v[14:15], v[228:229], v[146:147] op_sel_hi:[1,0,1]
	v_pk_fma_f32 v[16:17], v[144:145], v[230:231], v[16:17] op_sel_hi:[1,0,1] neg_lo:[1,0,0] neg_hi:[1,0,0]
	v_mul_f32_e32 v22, 0xbfb8aa3b, v14
	v_exp_f32_e32 v24, v22
	v_mul_f32_e32 v22, 0xbfb8aa3b, v15
	v_exp_f32_e32 v25, v22
	v_mad_i64_i32 v[22:23], s[38:39], v31, s65, v[158:159]
	v_add_f32_e32 v24, 1.0, v24
	v_add_f32_e32 v25, 1.0, v25
	v_rcp_f32_e32 v24, v24
	v_rcp_f32_e32 v25, v25
	v_pk_fma_f32 v[10:11], v[10:11], v[228:229], v[134:135] op_sel_hi:[1,0,1]
	v_pk_fma_f32 v[16:17], v[16:17], v[228:229], v[148:149] op_sel_hi:[1,0,1]
	global_store_dwordx4 v[22:23], v[18:21], off sc1
	v_pk_mul_f32 v[14:15], v[14:15], v[24:25]
	v_pk_fma_f32 v[12:13], v[140:141], v[230:231], v[12:13] op_sel_hi:[1,0,1] neg_lo:[1,0,0] neg_hi:[1,0,0]
	v_mul_f32_e32 v18, 0xbfb8aa3b, v16
	v_pk_mul_f32 v[10:11], v[10:11], v[14:15]
	v_mul_f32_e32 v14, 0xbfb8aa3b, v17
	v_exp_f32_e32 v18, v18
	v_exp_f32_e32 v15, v14
	v_pk_fma_f32 v[6:7], v[122:123], v[230:231], v[6:7] op_sel_hi:[1,0,1] neg_lo:[1,0,0] neg_hi:[1,0,0]
	v_pk_fma_f32 v[12:13], v[12:13], v[228:229], v[136:137] op_sel_hi:[1,0,1]
	v_add_f32_e32 v14, 1.0, v18
	v_add_f32_e32 v15, 1.0, v15
	v_rcp_f32_e32 v14, v14
	v_rcp_f32_e32 v15, v15
	v_pk_fma_f32 v[6:7], v[6:7], v[228:229], v[126:127] op_sel_hi:[1,0,1]
	v_pk_fma_f32 v[8:9], v[124:125], v[230:231], v[8:9] op_sel_hi:[1,0,1] neg_lo:[1,0,0] neg_hi:[1,0,0]
	v_mul_f32_e32 v18, 0xbfb8aa3b, v6
	v_pk_mul_f32 v[14:15], v[16:17], v[14:15]
	v_exp_f32_e32 v18, v18
	v_pk_mul_f32 v[12:13], v[12:13], v[14:15]
	v_mul_f32_e32 v15, 0xbfb8aa3b, v7
	v_exp_f32_e32 v15, v15
	v_pk_fma_f32 v[8:9], v[8:9], v[228:229], v[128:129] op_sel_hi:[1,0,1]
	v_add_f32_e32 v14, 1.0, v18
	v_mul_f32_e32 v16, 0xbfb8aa3b, v8
	v_add_f32_e32 v15, 1.0, v15
	v_mul_f32_e32 v17, 0xbfb8aa3b, v9
	v_rcp_f32_e32 v14, v14
	v_rcp_f32_e32 v15, v15
	v_exp_f32_e32 v16, v16
	v_exp_f32_e32 v17, v17
	v_pk_fma_f32 v[2:3], v[110:111], v[230:231], v[2:3] op_sel_hi:[1,0,1] neg_lo:[1,0,0] neg_hi:[1,0,0]
	v_pk_mul_f32 v[6:7], v[6:7], v[14:15]
	v_add_f32_e32 v14, 1.0, v16
	v_add_f32_e32 v15, 1.0, v17
	v_rcp_f32_e32 v14, v14
	v_rcp_f32_e32 v15, v15
	v_pk_fma_f32 v[2:3], v[2:3], v[228:229], v[114:115] op_sel_hi:[1,0,1]
	s_nop 0
	v_pk_mul_f32 v[6:7], v[2:3], v[6:7]
	v_pk_fma_f32 v[2:3], v[112:113], v[230:231], v[4:5] op_sel_hi:[1,0,1] neg_lo:[1,0,0] neg_hi:[1,0,0]
	v_pk_mul_f32 v[4:5], v[8:9], v[14:15]
	v_pk_fma_f32 v[2:3], v[2:3], v[228:229], v[116:117] op_sel_hi:[1,0,1]
	v_add_u32_e32 v14, 0xb0, v180
	v_pk_mul_f32 v[8:9], v[2:3], v[4:5]
	v_cvt_pk_bf16_f32 v2, v10, v11
	v_cvt_pk_bf16_f32 v3, v12, v13
	v_cvt_pk_bf16_f32 v4, v6, v7
	v_cvt_pk_bf16_f32 v5, v8, v9
	v_mad_i64_i32 v[6:7], s[38:39], v14, s65, v[158:159]
	global_store_dwordx4 v[6:7], v[2:5], off sc1
	v_writelane_b32 v255, s30, 46
	s_cbranch_vccnz .LBB0_941
	s_lshl_b32 s0, s22, 8
	s_add_i32 s0, s0, s45
	v_add_u32_e32 v2, s0, v177
	v_ashrrev_i32_e32 v3, 31, v2
	v_lshlrev_b64 v[4:5], 7, v[2:3]
	v_add_u32_e32 v2, 0x80, v2
	v_ashrrev_i32_e32 v3, 31, v2
	v_lshlrev_b64 v[2:3], 7, v[2:3]
	v_lshl_add_u64 v[4:5], s[94:95], 0, v[4:5]
	v_lshl_add_u64 v[2:3], s[94:95], 0, v[2:3]
	global_load_dwordx4 v[62:65], v[4:5], off
	global_load_dwordx4 v[58:61], v[4:5], off offset:16
	global_load_dwordx4 v[54:57], v[4:5], off offset:32
	global_load_dwordx4 v[50:53], v[4:5], off offset:48
	global_load_dwordx4 v[46:49], v[4:5], off offset:64
	global_load_dwordx4 v[42:45], v[4:5], off offset:80
	global_load_dwordx4 v[38:41], v[4:5], off offset:96
	global_load_dwordx4 v[34:37], v[4:5], off offset:112
	global_load_dwordx4 v[30:33], v[2:3], off
	global_load_dwordx4 v[26:29], v[2:3], off offset:16
	global_load_dwordx4 v[22:25], v[2:3], off offset:32
	global_load_dwordx4 v[18:21], v[2:3], off offset:48
	global_load_dwordx4 v[14:17], v[2:3], off offset:64
	global_load_dwordx4 v[10:13], v[2:3], off offset:80
	global_load_dwordx4 v[6:9], v[2:3], off offset:96
	s_nop 0
	global_load_dwordx4 v[2:5], v[2:3], off offset:112
	s_andn2_b64 vcc, exec, s[18:19]
	s_cbranch_vccnz .LBB0_940
	s_barrier
	s_branch .LBB0_940
